# stack11 + mLSTM stage A conv loop: the three boundary-row loads issued without individual waits (covered by the existing counted wait)
# speedup vs baseline: 1.0469x; 1.0469x over previous
.LBB0_522:
	v_ashrrev_i32_e32 v0, 2, v25
	v_and_b32_e32 v26, 0x7f, v25
	v_and_b32_e32 v0, 0xfffffe00, v0
	v_or3_b32 v14, s58, v0, v26
	v_ashrrev_i32_e32 v15, 31, v14
	v_lshlrev_b64 v[16:17], 2, v[14:15]
	v_lshl_add_u64 v[4:5], s[12:13], 0, v[16:17]
	v_add_co_u32_e32 v6, vcc, 0x1000, v4
	v_lshl_add_u64 v[16:17], s[14:15], 0, v[16:17]
	s_nop 0
	v_addc_co_u32_e32 v7, vcc, 0, v5, vcc
	v_add_co_u32_e32 v8, vcc, 0x2000, v4
	v_lshrrev_b32_e32 v0, 4, v25
	s_nop 0
	v_addc_co_u32_e32 v9, vcc, 0, v5, vcc
	v_add_co_u32_e32 v18, vcc, 0x3000, v4
	v_and_b32_e32 v27, 0x78, v0
	s_nop 0
	v_addc_co_u32_e32 v19, vcc, 0, v5, vcc
	global_load_dword v4, v[4:5], off
	s_nop 0
	global_load_dword v6, v[6:7], off
	s_nop 0
	global_load_dword v8, v[8:9], off
	s_nop 0
	global_load_dword v10, v[18:19], off
	global_load_dword v12, v[16:17], off
	v_add_u32_e32 v5, s59, v27
	v_lshl_add_u64 v[18:19], v[14:15], 1, s[28:29]
	v_cmp_lt_i32_e32 vcc, -1, v5
	v_mov_b32_e32 v219, 0
	v_mov_b32_e32 v220, 0
	v_mov_b32_e32 v221, 0
	s_and_saveexec_b64 s[4:5], vcc
	s_cbranch_execz .Lconv_a
	v_mad_u64_u32 v[16:17], s[6:7], v5, s49, v[18:19]
	global_load_ushort v219, v[16:17], off
	v_or_b32_e32 v0, 2, v5
	v_mad_u64_u32 v[28:29], s[6:7], v0, s49, v[18:19]
	global_load_ushort v221, v[28:29], off
.Lconv_a:
	s_or_b64 exec, exec, s[4:5]
	v_cmp_lt_i32_e64 s[4:5], -2, v5
	s_and_saveexec_b64 s[6:7], s[4:5]
	s_cbranch_execz .Lconv_b
	v_add_u32_e32 v0, 1, v5
	v_mad_u64_u32 v[14:15], s[4:5], v0, s49, v[18:19]
	global_load_ushort v220, v[14:15], off

.LBB0_526:
	v_or_b32_e32 v40, s56, v27
	v_mul_u32_u24_e32 v0, 0x1800, v40
	v_lshl_add_u64 v[28:29], v[18:19], 0, v[0:1]
	v_add_u32_e32 v0, 4, v5
	v_mad_u64_u32 v[30:31], s[4:5], v0, s49, v[18:19]
	v_add_u32_e32 v0, 5, v5
	v_mad_u64_u32 v[32:33], s[4:5], v0, s49, v[18:19]
	v_add_u32_e32 v0, 6, v5
	v_mad_u64_u32 v[34:35], s[4:5], v0, s49, v[18:19]
	global_load_ushort v0, v[28:29], off
	global_load_ushort v7, v[32:33], off
	global_load_ushort v9, v[34:35], off
	global_load_ushort v15, v[30:31], off
	v_add_u32_e32 v28, 7, v5
	v_add_u32_e32 v30, 9, v5
	v_mad_u64_u32 v[28:29], s[4:5], v28, s49, v[18:19]
	v_mad_u64_u32 v[30:31], s[4:5], v30, s49, v[18:19]
	global_load_ushort v34, v[28:29], off
	global_load_ushort v35, v[30:31], off
	v_add_u32_e32 v28, 8, v5
	v_add_u32_e32 v5, 10, v5
	v_mad_u64_u32 v[28:29], s[4:5], v28, s49, v[18:19]
	v_mad_u64_u32 v[18:19], s[4:5], v5, s49, v[18:19]
	global_load_ushort v36, v[28:29], off
	global_load_ushort v37, v[18:19], off
	s_waitcnt vmcnt(8)
	v_lshlrev_b32_e32 v16, 16, v219
	v_lshlrev_b32_e32 v14, 16, v220
	v_lshlrev_b32_e32 v17, 16, v221
	v_pk_fma_f32 v[18:19], v[4:5], v[16:17], v[12:13] op_sel_hi:[0,1,0]
	v_mov_b32_e32 v16, v17
	s_waitcnt vmcnt(7)
	v_lshlrev_b32_e32 v28, 16, v0
	s_waitcnt vmcnt(6)
	v_lshlrev_b32_e32 v29, 16, v7
	s_waitcnt vmcnt(5)
	v_lshlrev_b32_e32 v31, 16, v9
	s_waitcnt vmcnt(4)
	v_lshlrev_b32_e32 v30, 16, v15
	v_mov_b32_e32 v15, v28
	v_mov_b32_e32 v17, v30
	v_pk_fma_f32 v[18:19], v[6:7], v[14:15], v[18:19] op_sel_hi:[0,1,1]
	v_pk_fma_f32 v[14:15], v[4:5], v[14:15], v[12:13] op_sel_hi:[0,1,0]
	v_pk_fma_f32 v[18:19], v[8:9], v[16:17], v[18:19] op_sel_hi:[0,1,1]
	v_pk_fma_f32 v[14:15], v[6:7], v[16:17], v[14:15] op_sel_hi:[0,1,1]
	v_pk_fma_f32 v[16:17], v[10:11], v[28:29], v[18:19] op_sel_hi:[0,1,1]
	v_pk_fma_f32 v[14:15], v[8:9], v[28:29], v[14:15] op_sel_hi:[0,1,1]
	v_mul_f32_e32 v0, 0xbfb8aa3b, v16
	v_mul_f32_e32 v5, 0xbfb8aa3b, v17
	v_pk_fma_f32 v[18:19], v[10:11], v[30:31], v[14:15] op_sel_hi:[0,1,1]
	v_exp_f32_e32 v14, v0
	v_exp_f32_e32 v15, v5
	v_mul_f32_e32 v0, 0xbfb8aa3b, v18
	v_mul_f32_e32 v5, 0xbfb8aa3b, v19
	v_exp_f32_e32 v32, v0
	v_exp_f32_e32 v33, v5
	v_pk_add_f32 v[14:15], v[14:15], 1.0 op_sel_hi:[1,0]
	s_waitcnt vmcnt(3)
	v_lshlrev_b32_e32 v34, 16, v34
	v_div_scale_f32 v0, s[4:5], v15, v15, v17
	v_pk_add_f32 v[32:33], v[32:33], 1.0 op_sel_hi:[1,0]
	v_div_scale_f32 v7, s[4:5], v14, v14, v16
	v_rcp_f32_e32 v28, v0
	v_rcp_f32_e32 v38, v7
	v_div_scale_f32 v39, s[6:7], v33, v33, v19
	v_div_scale_f32 v42, s[8:9], v32, v32, v18
	v_rcp_f32_e32 v44, v39
	v_rcp_f32_e32 v45, v42
	v_fma_f32 v46, -v0, v28, 1.0
	v_div_scale_f32 v5, vcc, v17, v15, v17
	v_fma_f32 v47, -v7, v38, 1.0
	v_fmac_f32_e32 v28, v46, v28
	v_div_scale_f32 v9, s[4:5], v16, v14, v16
	v_fmac_f32_e32 v38, v47, v38
	v_fma_f32 v46, -v39, v44, 1.0
	v_mul_f32_e32 v48, v5, v28
	v_div_scale_f32 v41, s[6:7], v19, v33, v19
	v_fma_f32 v47, -v42, v45, 1.0
	v_mul_f32_e32 v49, v9, v38
	v_fmac_f32_e32 v44, v46, v44
	v_fma_f32 v46, -v0, v48, v5
	v_fmac_f32_e32 v45, v47, v45
	v_fma_f32 v47, -v7, v49, v9
	v_mul_f32_e32 v50, v41, v44
	v_fmac_f32_e32 v48, v46, v28
	v_fmac_f32_e32 v49, v47, v38
	v_fma_f32 v46, -v39, v50, v41
	v_fma_f32 v0, -v0, v48, v5
	v_fma_f32 v5, -v7, v49, v9
	v_fmac_f32_e32 v50, v46, v44
	v_div_fmas_f32 v0, v0, v28, v48
	s_mov_b64 vcc, s[4:5]
	v_fma_f32 v7, -v39, v50, v41
	v_div_fixup_f32 v15, v0, v15, v17
	v_div_fmas_f32 v0, v5, v38, v49
	s_mov_b64 vcc, s[6:7]
	v_div_fixup_f32 v14, v0, v14, v16
	v_div_fmas_f32 v0, v7, v44, v50
	s_waitcnt vmcnt(2)
	v_lshlrev_b32_e32 v35, 16, v35
	v_div_fixup_f32 v5, v0, v33, v19
	s_waitcnt vmcnt(1)
	v_lshlrev_b32_e32 v16, 16, v36
	s_waitcnt vmcnt(0)
	v_lshlrev_b32_e32 v17, 16, v37
	v_pk_fma_f32 v[36:37], v[4:5], v[30:31], v[12:13] op_sel_hi:[0,1,0]
	v_pk_mov_b32 v[28:29], v[28:29], v[34:35] op_sel:[1,0]
	v_pk_mov_b32 v[30:31], v[30:31], v[16:17] op_sel:[1,0]
	v_pk_fma_f32 v[36:37], v[6:7], v[28:29], v[36:37] op_sel_hi:[0,1,1]
	v_pk_fma_f32 v[36:37], v[8:9], v[30:31], v[36:37] op_sel_hi:[0,1,1]
	v_pk_fma_f32 v[36:37], v[10:11], v[34:35], v[36:37] op_sel_hi:[0,1,1]
	v_mul_f32_e32 v0, 0xbfb8aa3b, v36
	v_exp_f32_e32 v38, v0
	v_mul_f32_e32 v0, 0xbfb8aa3b, v37
	v_exp_f32_e32 v39, v0
	v_pk_fma_f32 v[28:29], v[4:5], v[28:29], v[12:13] op_sel_hi:[0,1,0]
	v_pk_fma_f32 v[6:7], v[6:7], v[30:31], v[28:29] op_sel_hi:[0,1,1]
	v_div_scale_f32 v43, s[8:9], v18, v32, v18
	v_pk_add_f32 v[38:39], v[38:39], 1.0 op_sel_hi:[1,0]
	v_pk_fma_f32 v[6:7], v[8:9], v[34:35], v[6:7] op_sel_hi:[0,1,1]
	v_mul_f32_e32 v51, v43, v45
	v_pk_fma_f32 v[8:9], v[10:11], v[16:17], v[6:7] op_sel_hi:[0,1,1]
	v_div_scale_f32 v10, s[4:5], v39, v39, v37
	v_fma_f32 v0, -v42, v51, v43
	v_mul_f32_e32 v4, 0xbfb8aa3b, v8
	v_rcp_f32_e32 v12, v10
	v_fmac_f32_e32 v51, v0, v45
	v_exp_f32_e32 v6, v4
	v_mul_f32_e32 v4, 0xbfb8aa3b, v9
	v_fma_f32 v0, -v42, v51, v43
	v_exp_f32_e32 v7, v4
	s_mov_b64 vcc, s[8:9]
	v_div_fmas_f32 v0, v0, v45, v51
	v_div_fixup_f32 v4, v0, v32, v18
	v_fma_f32 v0, -v10, v12, 1.0
	v_fmac_f32_e32 v12, v0, v12
	v_div_scale_f32 v0, vcc, v37, v39, v37
	v_pk_add_f32 v[16:17], v[6:7], 1.0 op_sel_hi:[1,0]
	v_mul_f32_e32 v6, v0, v12
	v_fma_f32 v7, -v10, v6, v0
	v_fmac_f32_e32 v6, v7, v12
	v_fma_f32 v0, -v10, v6, v0
	v_div_scale_f32 v10, s[4:5], v38, v38, v36
	v_rcp_f32_e32 v18, v10
	v_div_fmas_f32 v0, v0, v12, v6
	v_div_fixup_f32 v7, v0, v39, v37
	v_fma_f32 v0, -v10, v18, 1.0
	v_fmac_f32_e32 v18, v0, v18
	v_div_scale_f32 v0, vcc, v36, v38, v36
	v_mul_f32_e32 v6, v0, v18
	v_fma_f32 v12, -v10, v6, v0
	v_fmac_f32_e32 v6, v12, v18
	v_fma_f32 v0, -v10, v6, v0
	v_div_scale_f32 v10, s[4:5], v17, v17, v9
	v_rcp_f32_e32 v12, v10
	v_div_fmas_f32 v0, v0, v18, v6
	v_div_fixup_f32 v6, v0, v38, v36
	v_fma_f32 v0, -v10, v12, 1.0
	v_fmac_f32_e32 v12, v0, v12
	v_div_scale_f32 v0, vcc, v9, v17, v9
	v_mul_f32_e32 v18, v0, v12
	v_fma_f32 v19, -v10, v18, v0
	v_fmac_f32_e32 v18, v19, v12
	v_fma_f32 v0, -v10, v18, v0
	v_div_scale_f32 v10, s[4:5], v16, v16, v8
	v_rcp_f32_e32 v19, v10
	v_div_fmas_f32 v0, v0, v12, v18
	v_div_fixup_f32 v9, v0, v17, v9
	v_fma_f32 v0, -v10, v19, 1.0
	v_fmac_f32_e32 v19, v0, v19
	v_div_scale_f32 v0, vcc, v8, v16, v8
	v_mul_f32_e32 v12, v0, v19
	v_fma_f32 v17, -v10, v12, v0
	v_fmac_f32_e32 v12, v17, v19
	v_fma_f32 v0, -v10, v12, v0
	v_div_fmas_f32 v0, v0, v19, v12
	v_div_fixup_f32 v8, v0, v16, v8
	v_lshlrev_b32_e32 v0, 9, v40
	v_or3_b32 v0, s58, v0, v26
	v_cmp_lt_u32_e32 vcc, s50, v25
	v_lshlrev_b32_e32 v0, 1, v0
	s_and_saveexec_b64 s[4:5], vcc
	s_xor_b64 s[4:5], exec, s[4:5]
	s_cbranch_execz .LBB0_528
	v_bfe_u32 v12, v14, 16, 1
	v_add3_u32 v12, v14, v12, s51
	global_store_short_d16_hi v0, v12, s[34:35]
	v_bfe_u32 v12, v4, 16, 1
	v_add3_u32 v12, v4, v12, s51
	global_store_short_d16_hi v0, v12, s[34:35] offset:1024
	v_bfe_u32 v12, v15, 16, 1
	v_add3_u32 v12, v15, v12, s51
	global_store_short_d16_hi v0, v12, s[34:35] offset:2048
	v_bfe_u32 v12, v5, 16, 1
	v_lshl_add_u64 v[16:17], s[34:35], 0, v[0:1]
	v_add3_u32 v12, v5, v12, s51
	global_store_short_d16_hi v0, v12, s[34:35] offset:3072
	v_bfe_u32 v0, v6, 16, 1
	v_add_co_u32_e32 v28, vcc, s48, v16
	v_add3_u32 v0, v6, v0, s51
	s_nop 0
	v_addc_co_u32_e32 v29, vcc, 0, v17, vcc
	global_store_short_d16_hi v[28:29], v0, off
	v_bfe_u32 v0, v8, 16, 1
	v_add3_u32 v0, v8, v0, s51
	global_store_short_d16_hi v[28:29], v0, off offset:1024
	v_bfe_u32 v0, v7, 16, 1
	v_add3_u32 v0, v7, v0, s51
	v_lshl_add_u32 v10, v27, 2, 0
	global_store_short_d16_hi v[28:29], v0, off offset:2048
	v_bfe_u32 v0, v9, 16, 1
	ds_read_b128 v[16:19], v10
	v_add3_u32 v0, v9, v0, s51
	global_store_short_d16_hi v[28:29], v0, off offset:3072
	ds_read_b128 v[28:31], v10 offset:16
	s_waitcnt lgkmcnt(1)
	v_mov_b32_e32 v33, v18
	v_mov_b32_e32 v18, v17
	v_mov_b32_e32 v32, v16
	v_pk_mul_f32 v[4:5], v[4:5], v[18:19]
	s_waitcnt lgkmcnt(0)
	v_mov_b32_e32 v16, v28
	v_mov_b32_e32 v17, v30
	v_mov_b32_e32 v30, v29
	v_pk_mul_f32 v[6:7], v[6:7], v[16:17]
	v_pk_mul_f32 v[8:9], v[8:9], v[30:31]
	v_bfe_u32 v12, v5, 16, 1
	v_bfe_u32 v16, v4, 16, 1
	v_pk_mul_f32 v[14:15], v[14:15], v[32:33]
	v_bfe_u32 v0, v9, 16, 1
	v_bfe_u32 v10, v8, 16, 1
	v_add3_u32 v4, v4, v16, s51
	v_add3_u32 v5, v5, v12, s51
	v_bfe_u32 v12, v6, 16, 1
	v_bfe_u32 v16, v7, 16, 1
	v_add3_u32 v8, v8, v10, s51
	v_add3_u32 v0, v9, v0, s51
	v_bfe_u32 v9, v14, 16, 1
	v_bfe_u32 v10, v15, 16, 1
	v_add3_u32 v7, v7, v16, s51
	v_add3_u32 v6, v6, v12, s51
	v_add3_u32 v10, v15, v10, s51
	v_add3_u32 v9, v14, v9, s51
	v_lshrrev_b32_e32 v6, 16, v6
	v_lshrrev_b32_e32 v7, 16, v7
	v_lshrrev_b32_e32 v9, 16, v9
	v_lshrrev_b32_e32 v10, 16, v10
	v_and_or_b32 v7, v0, s52, v7
	v_and_or_b32 v6, v8, s52, v6
	v_mul_u32_u24_e32 v0, 0x110, v26
	v_lshlrev_b32_e32 v8, 1, v27
	v_and_or_b32 v5, v5, s52, v10
	v_and_or_b32 v4, v4, s52, v9
	v_add3_u32 v0, 0, v0, v8
	ds_write_b128 v0, v[4:7] offset:4096
